# attention: running-max tree removed from the key loop; rescale check on the lane row-sum after exp (reference initialised from tile 0 max in the peel), rescale applied to P post-exp
# speedup vs baseline: 1.0333x; 1.0333x over previous
.Lat_noprio:
	v_mov_b32_e32 v96, 0
	v_mov_b32_e32 v97, 0
	v_mov_b32_e32 v98, 0
	v_mov_b32_e32 v99, 0
	v_mov_b32_e32 v100, 0
	v_mov_b32_e32 v101, 0
	v_mov_b32_e32 v102, 0
	v_mov_b32_e32 v103, 0
	v_mov_b32_e32 v112, 0
	v_mov_b32_e32 v113, 0
	v_mov_b32_e32 v114, 0
	v_mov_b32_e32 v115, 0
	v_mov_b32_e32 v116, 0
	v_mov_b32_e32 v117, 0
	v_mov_b32_e32 v118, 0
	v_mov_b32_e32 v119, 0
	v_sub_u32_e32 v228, 1, v192
	v_mul_u32_u24_e32 v228, 0xffff, v228
	v_and_b32_e32 v240, 0x3f80, v228
	v_mov_b32_e32 v241, 0
	v_mov_b32_e32 v242, 0
	v_mov_b32_e32 v243, 0
	v_mov_b32_e32 v245, 0
	v_mov_b32_e32 v246, 0
	v_mov_b32_e32 v247, 0
	v_mov_b32_e32 v249, 0
	v_mov_b32_e32 v250, 0
	v_mov_b32_e32 v251, 0
	v_add3_u32 v224, s34, v183, v128
	ds_read_b128 v[212:215], v224 offset:0
	ds_read_b128 v[216:219], v224 offset:32
	ds_read_b128 v[220:223], v224 offset:64
	s_waitcnt lgkmcnt(2)
	v_mfma_f32_32x32x16_bf16 v[64:79], v[212:215], v[130:133], 0
	v_mfma_f32_32x32x16_bf16 v[80:95], v[212:215], v[138:141], 0
	ds_read_b128 v[212:215], v224 offset:96
	s_waitcnt lgkmcnt(2)
	v_mfma_f32_32x32x16_bf16 v[64:79], v[216:219], v[134:137], v[64:79]
	v_mfma_f32_32x32x16_bf16 v[80:95], v[216:219], v[142:145], v[80:95]
	ds_read_b128 v[216:219], v224 offset:128
	s_waitcnt lgkmcnt(2)
	v_mfma_f32_32x32x16_bf16 v[64:79], v[220:223], v[146:149], v[64:79]
	v_mfma_f32_32x32x16_bf16 v[80:95], v[220:223], v[154:157], v[80:95]
	ds_read_b128 v[220:223], v224 offset:160
	s_waitcnt lgkmcnt(2)
	v_mfma_f32_32x32x16_bf16 v[64:79], v[212:215], v[150:153], v[64:79]
	v_mfma_f32_32x32x16_bf16 v[80:95], v[212:215], v[158:161], v[80:95]
	s_waitcnt lgkmcnt(1)
	v_mfma_f32_32x32x16_bf16 v[64:79], v[216:219], v[162:165], v[64:79]
	v_mfma_f32_32x32x16_bf16 v[80:95], v[216:219], v[170:173], v[80:95]
	s_waitcnt lgkmcnt(0)
	v_mfma_f32_32x32x16_bf16 v[64:79], v[220:223], v[166:169], v[64:79]
	v_mfma_f32_32x32x16_bf16 v[80:95], v[220:223], v[174:177], v[80:95]
	s_nop 15
	s_nop 3
	v_max3_f32 v226, v64, v65, v66
	v_max3_f32 v227, v67, v68, v69
	v_max3_f32 v226, v226, v70, v71
	v_max3_f32 v227, v227, v72, v73
	v_max3_f32 v226, v226, v74, v75
	v_max3_f32 v227, v227, v76, v77
	v_max3_f32 v226, v226, v78, v79
	v_max_f32_e32 v226, v226, v227
	v_mov_b32_e32 v227, v226
	s_nop 1
	v_permlane32_swap_b32_e32 v226, v227
	v_max_f32_e32 v226, v226, v227
	v_cvt_pk_bf16_f32 v227, v226, v226
	v_and_b32_e32 v194, 0xffff0000, v227
	v_xor_b32_e32 v227, 0x80000000, v194
	v_lshrrev_b32_e32 v227, 16, v227
	v_and_b32_e32 v244, v228, v227
	v_max3_f32 v236, v80, v81, v82
	v_max3_f32 v237, v83, v84, v85
	v_max3_f32 v236, v236, v86, v87
	v_max3_f32 v237, v237, v88, v89
	v_max3_f32 v236, v236, v90, v91
	v_max3_f32 v237, v237, v92, v93
	v_max3_f32 v236, v236, v94, v95
	v_max_f32_e32 v236, v236, v237
	v_mov_b32_e32 v237, v236
	s_nop 1
	v_permlane32_swap_b32_e32 v236, v237
	v_max_f32_e32 v236, v236, v237
	v_cvt_pk_bf16_f32 v237, v236, v236
	v_and_b32_e32 v195, 0xffff0000, v237
	v_xor_b32_e32 v237, 0x80000000, v195
	v_lshrrev_b32_e32 v237, 16, v237
	v_and_b32_e32 v248, v228, v237
	s_nop 3
	v_mfma_f32_32x32x16_bf16 v[64:79], v[240:243], v[244:247], v[64:79]
	v_mfma_f32_32x32x16_bf16 v[80:95], v[240:243], v[248:251], v[80:95]
	v_add3_u32 v225, s34, v187, v128
	ds_read_b128 v[196:199], v225 offset:13376
	ds_read_b128 v[200:203], v225 offset:17984
	ds_read_b128 v[204:207], v225 offset:13408
	ds_read_b128 v[208:211], v225 offset:18016
	s_nop 7
	s_nop 3
.Lat_loop:
	v_add3_u32 v224, s34, v183, v128
	ds_read_b128 v[212:215], v224 offset:6656
	ds_read_b128 v[216:219], v224 offset:6688
	ds_read_b128 v[220:223], v224 offset:6720
	s_waitcnt lgkmcnt(6)
	v_mfma_f32_32x32x16_bf16 v[16:31], v[196:199], v[96:99], v[16:31]
	v_exp_f32_e32 v64, v64
	v_exp_f32_e32 v65, v65
	v_exp_f32_e32 v66, v66
	v_exp_f32_e32 v67, v67
	s_waitcnt lgkmcnt(5)
	v_mfma_f32_32x32x16_bf16 v[48:63], v[200:203], v[96:99], v[48:63]
	v_exp_f32_e32 v68, v68
	v_exp_f32_e32 v69, v69
	v_add_f32_e32 v230, v64, v65
	v_exp_f32_e32 v70, v70
	s_waitcnt lgkmcnt(4)
	v_mfma_f32_32x32x16_bf16 v[16:31], v[204:207], v[100:103], v[16:31]
	v_exp_f32_e32 v71, v71
	v_add_f32_e32 v231, v66, v67
	v_exp_f32_e32 v72, v72
	v_exp_f32_e32 v73, v73
	s_waitcnt lgkmcnt(3)
	v_mfma_f32_32x32x16_bf16 v[48:63], v[208:211], v[100:103], v[48:63]
	v_add_f32_e32 v230, v230, v68
	v_add_f32_e32 v231, v231, v69
	v_exp_f32_e32 v74, v74
	v_exp_f32_e32 v75, v75
	v_add_f32_e32 v230, v230, v70
	v_add_f32_e32 v231, v231, v71
	v_mfma_f32_32x32x16_bf16 v[32:47], v[196:199], v[112:115], v[32:47]
	v_exp_f32_e32 v76, v76
	v_exp_f32_e32 v77, v77
	v_add_f32_e32 v230, v230, v72
	v_add_f32_e32 v231, v231, v73
	v_mfma_f32_32x32x16_bf16 v[0:15], v[200:203], v[112:115], v[0:15]
	v_exp_f32_e32 v78, v78
	v_exp_f32_e32 v79, v79
	v_add_f32_e32 v230, v230, v74
	v_add_f32_e32 v231, v231, v75
	v_mfma_f32_32x32x16_bf16 v[32:47], v[204:207], v[116:119], v[32:47]
	v_add_f32_e32 v230, v230, v76
	v_add_f32_e32 v231, v231, v77
	v_add_f32_e32 v230, v230, v78
	v_add_f32_e32 v231, v231, v79
	v_mfma_f32_32x32x16_bf16 v[0:15], v[208:211], v[116:119], v[0:15]
	v_add_f32_e32 v230, v230, v231
	v_add3_u32 v225, s34, v187, v128
	ds_read_b128 v[196:199], v225 offset:13312
	ds_read_b128 v[200:203], v225 offset:17920
	ds_read_b128 v[204:207], v225 offset:13344
	ds_read_b128 v[208:211], v225 offset:17952
	v_cmp_lt_f32_e32 vcc, 0x45800000, v230
	s_cbranch_vccnz .Lat_resc_aE
.Lat_back_aE:
	v_add_f32_e32 v191, v191, v230
	v_cvt_pk_bf16_f32 v64, v64, v65
	v_mfma_f32_32x32x16_bf16 v[96:111], v[240:243], v[244:247], 0
	v_cvt_pk_bf16_f32 v65, v66, v67
	v_cvt_pk_bf16_f32 v66, v68, v69
	v_cvt_pk_bf16_f32 v67, v70, v71
	s_waitcnt lgkmcnt(6)
	v_mfma_f32_32x32x16_bf16 v[96:111], v[212:215], v[130:133], v[96:111]
	v_cvt_pk_bf16_f32 v68, v72, v73
	v_cvt_pk_bf16_f32 v69, v74, v75
	v_cvt_pk_bf16_f32 v70, v76, v77
	v_cvt_pk_bf16_f32 v71, v78, v79
	v_mfma_f32_32x32x16_bf16 v[112:127], v[212:215], v[138:141], 0
	ds_read_b128 v[212:215], v224 offset:6752
	v_exp_f32_e32 v80, v80
	v_exp_f32_e32 v81, v81
	v_exp_f32_e32 v82, v82
	s_waitcnt lgkmcnt(6)
	v_mfma_f32_32x32x16_bf16 v[96:111], v[216:219], v[134:137], v[96:111]
	v_exp_f32_e32 v83, v83
	v_exp_f32_e32 v84, v84
	v_exp_f32_e32 v85, v85
	v_add_f32_e32 v230, v80, v81
	v_mfma_f32_32x32x16_bf16 v[112:127], v[216:219], v[142:145], v[112:127]
	ds_read_b128 v[216:219], v224 offset:6784
	v_exp_f32_e32 v86, v86
	v_exp_f32_e32 v87, v87
	v_add_f32_e32 v231, v82, v83
	s_waitcnt lgkmcnt(6)
	v_mfma_f32_32x32x16_bf16 v[96:111], v[220:223], v[146:149], v[96:111]
	v_exp_f32_e32 v88, v88
	v_exp_f32_e32 v89, v89
	v_add_f32_e32 v230, v230, v84
	v_add_f32_e32 v231, v231, v85
	v_mfma_f32_32x32x16_bf16 v[112:127], v[220:223], v[154:157], v[112:127]
	ds_read_b128 v[220:223], v224 offset:6816
	v_exp_f32_e32 v90, v90
	v_exp_f32_e32 v91, v91
	v_add_f32_e32 v230, v230, v86
	s_waitcnt lgkmcnt(2)
	v_mfma_f32_32x32x16_bf16 v[96:111], v[212:215], v[150:153], v[96:111]
	v_add_f32_e32 v231, v231, v87
	v_exp_f32_e32 v92, v92
	v_exp_f32_e32 v93, v93
	v_add_f32_e32 v230, v230, v88
	v_mfma_f32_32x32x16_bf16 v[112:127], v[212:215], v[158:161], v[112:127]
	v_add_f32_e32 v231, v231, v89
	v_exp_f32_e32 v94, v94
	v_exp_f32_e32 v95, v95
	s_waitcnt lgkmcnt(1)
	v_mfma_f32_32x32x16_bf16 v[96:111], v[216:219], v[162:165], v[96:111]
	v_add_f32_e32 v230, v230, v90
	v_add_f32_e32 v231, v231, v91
	v_add_f32_e32 v230, v230, v92
	v_add_f32_e32 v231, v231, v93
	v_mfma_f32_32x32x16_bf16 v[112:127], v[216:219], v[170:173], v[112:127]
	v_add_f32_e32 v230, v230, v94
	v_add_f32_e32 v231, v231, v95
	v_add_f32_e32 v230, v230, v231
	s_waitcnt lgkmcnt(0)
	v_mfma_f32_32x32x16_bf16 v[96:111], v[220:223], v[166:169], v[96:111]
	v_cmp_lt_f32_e32 vcc, 0x45800000, v230
	s_cbranch_vccnz .Lat_resc_bE
.Lat_back_bE:
	v_add_f32_e32 v193, v193, v230
	v_cvt_pk_bf16_f32 v80, v80, v81
	v_cvt_pk_bf16_f32 v81, v82, v83
	v_mfma_f32_32x32x16_bf16 v[112:127], v[220:223], v[174:177], v[112:127]
	v_cvt_pk_bf16_f32 v82, v84, v85
	v_cvt_pk_bf16_f32 v83, v86, v87
	v_cvt_pk_bf16_f32 v84, v88, v89
	v_mfma_f32_32x32x16_bf16 v[112:127], v[240:243], v[248:251], v[112:127]
	v_cvt_pk_bf16_f32 v85, v90, v91
	v_cvt_pk_bf16_f32 v86, v92, v93
	v_cvt_pk_bf16_f32 v87, v94, v95
	s_waitcnt vmcnt(0)
	s_barrier
	s_cmpk_gt_u32 s27, 0x81
	s_cbranch_scc1 .Lat_dma_endL
	s_cmp_lt_u32 s27, 2
	s_cselect_b32 s14, s10, s11
	s_add_i32 s14, s14, s24
	s_and_b64 vcc, exec, s[4:5]
	s_cbranch_vccnz .Lat_dmaL_0
	v_mad_u64_u32 v[234:235], s[16:17], v182, s14, v[180:181]
	s_add_i32 m0, s25, s19
	s_nop 0
	global_load_lds_dwordx4 v[234:235], off

.Lat_dmaL_2:
.Lat_dma_endL:
	v_add3_u32 v224, s26, v183, v128
	ds_read_b128 v[212:215], v224 offset:0
	ds_read_b128 v[216:219], v224 offset:32
	ds_read_b128 v[220:223], v224 offset:64
	v_mfma_f32_32x32x16_bf16 v[16:31], v[196:199], v[64:67], v[16:31]
	v_exp_f32_e32 v96, v96
	v_exp_f32_e32 v97, v97
	v_exp_f32_e32 v98, v98
	v_exp_f32_e32 v99, v99
	v_mfma_f32_32x32x16_bf16 v[48:63], v[200:203], v[64:67], v[48:63]
	v_exp_f32_e32 v100, v100
	v_exp_f32_e32 v101, v101
	v_add_f32_e32 v230, v96, v97
	v_exp_f32_e32 v102, v102
	v_mfma_f32_32x32x16_bf16 v[16:31], v[204:207], v[68:71], v[16:31]
	v_exp_f32_e32 v103, v103
	v_add_f32_e32 v231, v98, v99
	v_exp_f32_e32 v104, v104
	v_exp_f32_e32 v105, v105
	v_mfma_f32_32x32x16_bf16 v[48:63], v[208:211], v[68:71], v[48:63]
	v_add_f32_e32 v230, v230, v100
	v_add_f32_e32 v231, v231, v101
	v_exp_f32_e32 v106, v106
	v_exp_f32_e32 v107, v107
	v_add_f32_e32 v230, v230, v102
	v_add_f32_e32 v231, v231, v103
	v_mfma_f32_32x32x16_bf16 v[32:47], v[196:199], v[80:83], v[32:47]
	v_exp_f32_e32 v108, v108
	v_exp_f32_e32 v109, v109
	v_add_f32_e32 v230, v230, v104
	v_add_f32_e32 v231, v231, v105
	v_mfma_f32_32x32x16_bf16 v[0:15], v[200:203], v[80:83], v[0:15]
	v_exp_f32_e32 v110, v110
	v_exp_f32_e32 v111, v111
	v_add_f32_e32 v230, v230, v106
	v_add_f32_e32 v231, v231, v107
	v_mfma_f32_32x32x16_bf16 v[32:47], v[204:207], v[84:87], v[32:47]
	v_add_f32_e32 v230, v230, v108
	v_add_f32_e32 v231, v231, v109
	v_add_f32_e32 v230, v230, v110
	v_add_f32_e32 v231, v231, v111
	v_mfma_f32_32x32x16_bf16 v[0:15], v[208:211], v[84:87], v[0:15]
	v_add_f32_e32 v230, v230, v231
	v_add3_u32 v225, s34, v187, v128
	ds_read_b128 v[196:199], v225 offset:13376
	ds_read_b128 v[200:203], v225 offset:17984
	ds_read_b128 v[204:207], v225 offset:13408
	ds_read_b128 v[208:211], v225 offset:18016
	v_cmp_lt_f32_e32 vcc, 0x45800000, v230
	s_cbranch_vccnz .Lat_resc_aO
.Lat_back_aO:
	v_add_f32_e32 v191, v191, v230
	v_cvt_pk_bf16_f32 v96, v96, v97
	v_mfma_f32_32x32x16_bf16 v[64:79], v[240:243], v[244:247], 0
	v_cvt_pk_bf16_f32 v97, v98, v99
	v_cvt_pk_bf16_f32 v98, v100, v101
	v_cvt_pk_bf16_f32 v99, v102, v103
	s_waitcnt lgkmcnt(6)
	v_mfma_f32_32x32x16_bf16 v[64:79], v[212:215], v[130:133], v[64:79]
	v_cvt_pk_bf16_f32 v100, v104, v105
	v_cvt_pk_bf16_f32 v101, v106, v107
	v_cvt_pk_bf16_f32 v102, v108, v109
	v_cvt_pk_bf16_f32 v103, v110, v111
	v_mfma_f32_32x32x16_bf16 v[80:95], v[212:215], v[138:141], 0
	ds_read_b128 v[212:215], v224 offset:96
	v_exp_f32_e32 v112, v112
	v_exp_f32_e32 v113, v113
	v_exp_f32_e32 v114, v114
	s_waitcnt lgkmcnt(6)
	v_mfma_f32_32x32x16_bf16 v[64:79], v[216:219], v[134:137], v[64:79]
	v_exp_f32_e32 v115, v115
	v_exp_f32_e32 v116, v116
	v_exp_f32_e32 v117, v117
	v_add_f32_e32 v230, v112, v113
	v_mfma_f32_32x32x16_bf16 v[80:95], v[216:219], v[142:145], v[80:95]
	ds_read_b128 v[216:219], v224 offset:128
	v_exp_f32_e32 v118, v118
	v_exp_f32_e32 v119, v119
	v_add_f32_e32 v231, v114, v115
	s_waitcnt lgkmcnt(6)
	v_mfma_f32_32x32x16_bf16 v[64:79], v[220:223], v[146:149], v[64:79]
	v_exp_f32_e32 v120, v120
	v_exp_f32_e32 v121, v121
	v_add_f32_e32 v230, v230, v116
	v_add_f32_e32 v231, v231, v117
	v_mfma_f32_32x32x16_bf16 v[80:95], v[220:223], v[154:157], v[80:95]
	ds_read_b128 v[220:223], v224 offset:160
	v_exp_f32_e32 v122, v122
	v_exp_f32_e32 v123, v123
	v_add_f32_e32 v230, v230, v118
	s_waitcnt lgkmcnt(2)
	v_mfma_f32_32x32x16_bf16 v[64:79], v[212:215], v[150:153], v[64:79]
	v_add_f32_e32 v231, v231, v119
	v_exp_f32_e32 v124, v124
	v_exp_f32_e32 v125, v125
	v_add_f32_e32 v230, v230, v120
	v_mfma_f32_32x32x16_bf16 v[80:95], v[212:215], v[158:161], v[80:95]
	v_add_f32_e32 v231, v231, v121
	v_exp_f32_e32 v126, v126
	v_exp_f32_e32 v127, v127
	s_waitcnt lgkmcnt(1)
	v_mfma_f32_32x32x16_bf16 v[64:79], v[216:219], v[162:165], v[64:79]
	v_add_f32_e32 v230, v230, v122
	v_add_f32_e32 v231, v231, v123
	v_add_f32_e32 v230, v230, v124
	v_add_f32_e32 v231, v231, v125
	v_mfma_f32_32x32x16_bf16 v[80:95], v[216:219], v[170:173], v[80:95]
	v_add_f32_e32 v230, v230, v126
	v_add_f32_e32 v231, v231, v127
	v_add_f32_e32 v230, v230, v231
	s_waitcnt lgkmcnt(0)
	v_mfma_f32_32x32x16_bf16 v[64:79], v[220:223], v[166:169], v[64:79]
	v_cmp_lt_f32_e32 vcc, 0x45800000, v230
	s_cbranch_vccnz .Lat_resc_bO
.Lat_back_bO:
	v_add_f32_e32 v193, v193, v230
	v_cvt_pk_bf16_f32 v112, v112, v113
	v_cvt_pk_bf16_f32 v113, v114, v115
	v_mfma_f32_32x32x16_bf16 v[80:95], v[220:223], v[174:177], v[80:95]
	v_cvt_pk_bf16_f32 v114, v116, v117
	v_cvt_pk_bf16_f32 v115, v118, v119
	v_cvt_pk_bf16_f32 v116, v120, v121
	v_mfma_f32_32x32x16_bf16 v[80:95], v[240:243], v[248:251], v[80:95]
	v_cvt_pk_bf16_f32 v117, v122, v123
	v_cvt_pk_bf16_f32 v118, v124, v125
	v_cvt_pk_bf16_f32 v119, v126, v127
	s_add_i32 s27, s27, 1
	s_add_i32 s24, s24, 64
	s_mov_b32 s14, s34
	s_mov_b32 s34, s26
	s_mov_b32 s26, s25
	s_mov_b32 s25, s14
	s_cmpk_lg_i32 s27, 0x84
	s_cbranch_scc1 .Lat_loop
	s_waitcnt lgkmcnt(3)
	v_mfma_f32_32x32x16_bf16 v[16:31], v[196:199], v[96:99], v[16:31]
	s_waitcnt lgkmcnt(2)
	v_mfma_f32_32x32x16_bf16 v[48:63], v[200:203], v[96:99], v[48:63]
	s_waitcnt lgkmcnt(1)
	v_mfma_f32_32x32x16_bf16 v[16:31], v[204:207], v[100:103], v[16:31]
	s_waitcnt lgkmcnt(0)
	v_mfma_f32_32x32x16_bf16 v[48:63], v[208:211], v[100:103], v[48:63]
	v_mfma_f32_32x32x16_bf16 v[32:47], v[196:199], v[112:115], v[32:47]
	v_mfma_f32_32x32x16_bf16 v[0:15], v[200:203], v[112:115], v[0:15]
	v_mfma_f32_32x32x16_bf16 v[32:47], v[204:207], v[116:119], v[32:47]
	v_mfma_f32_32x32x16_bf16 v[0:15], v[208:211], v[116:119], v[0:15]
	s_branch .Lat_done
.Lat_resc_aE:
	s_nop 15
	v_max3_f32 v226, v64, v65, v66
	v_max3_f32 v227, v67, v68, v69
	v_max3_f32 v226, v226, v70, v71
	v_max3_f32 v227, v227, v72, v73
	v_max3_f32 v226, v226, v74, v75
	v_max3_f32 v227, v227, v76, v77
	v_max3_f32 v226, v226, v78, v79
	v_max_f32_e32 v226, v226, v227
	v_mov_b32_e32 v227, v226
	s_nop 1
	v_permlane32_swap_b32_e32 v226, v227
	v_max_f32_e32 v226, v226, v227
	v_max_f32_e32 v226, 1.0, v226
	v_log_f32_e32 v226, v226
	s_nop 0
	v_add_f32_e32 v227, v194, v226
	v_cvt_pk_bf16_f32 v227, v227, v227
	v_and_b32_e32 v227, 0xffff0000, v227
	v_sub_f32_e32 v229, v194, v227
	v_mov_b32_e32 v194, v227
	v_exp_f32_e32 v232, v229
	v_xor_b32_e32 v227, 0x80000000, v227
	v_lshrrev_b32_e32 v227, 16, v227
	v_and_b32_e32 v244, v228, v227
	v_mul_f32_e32 v64, v64, v232
	v_mul_f32_e32 v65, v65, v232
	v_mul_f32_e32 v66, v66, v232
	v_mul_f32_e32 v67, v67, v232
	v_mul_f32_e32 v68, v68, v232
	v_mul_f32_e32 v69, v69, v232
	v_mul_f32_e32 v70, v70, v232
	v_mul_f32_e32 v71, v71, v232
	v_mul_f32_e32 v72, v72, v232
	v_mul_f32_e32 v73, v73, v232
	v_mul_f32_e32 v74, v74, v232
	v_mul_f32_e32 v75, v75, v232
	v_mul_f32_e32 v76, v76, v232
	v_mul_f32_e32 v77, v77, v232
	v_mul_f32_e32 v78, v78, v232
	v_mul_f32_e32 v79, v79, v232
	v_mul_f32_e32 v230, v230, v232
	v_pk_mul_f32 v[16:17], v[16:17], v[232:233] op_sel_hi:[1,0]
	v_pk_mul_f32 v[18:19], v[18:19], v[232:233] op_sel_hi:[1,0]
	v_pk_mul_f32 v[20:21], v[20:21], v[232:233] op_sel_hi:[1,0]
	v_pk_mul_f32 v[22:23], v[22:23], v[232:233] op_sel_hi:[1,0]
	v_pk_mul_f32 v[24:25], v[24:25], v[232:233] op_sel_hi:[1,0]
	v_pk_mul_f32 v[26:27], v[26:27], v[232:233] op_sel_hi:[1,0]
	v_pk_mul_f32 v[28:29], v[28:29], v[232:233] op_sel_hi:[1,0]
	v_pk_mul_f32 v[30:31], v[30:31], v[232:233] op_sel_hi:[1,0]
	v_pk_mul_f32 v[48:49], v[48:49], v[232:233] op_sel_hi:[1,0]
	v_pk_mul_f32 v[50:51], v[50:51], v[232:233] op_sel_hi:[1,0]
	v_pk_mul_f32 v[52:53], v[52:53], v[232:233] op_sel_hi:[1,0]
	v_pk_mul_f32 v[54:55], v[54:55], v[232:233] op_sel_hi:[1,0]
	v_pk_mul_f32 v[56:57], v[56:57], v[232:233] op_sel_hi:[1,0]
	v_pk_mul_f32 v[58:59], v[58:59], v[232:233] op_sel_hi:[1,0]
	v_pk_mul_f32 v[60:61], v[60:61], v[232:233] op_sel_hi:[1,0]
	v_pk_mul_f32 v[62:63], v[62:63], v[232:233] op_sel_hi:[1,0]
	v_mul_f32_e32 v191, v191, v232
	s_branch .Lat_back_aE
.Lat_resc_bE:
	s_nop 15
	v_max3_f32 v236, v80, v81, v82
	v_max3_f32 v237, v83, v84, v85
	v_max3_f32 v236, v236, v86, v87
	v_max3_f32 v237, v237, v88, v89
	v_max3_f32 v236, v236, v90, v91
	v_max3_f32 v237, v237, v92, v93
	v_max3_f32 v236, v236, v94, v95
	v_max_f32_e32 v236, v236, v237
	v_mov_b32_e32 v237, v236
	s_nop 1
	v_permlane32_swap_b32_e32 v236, v237
	v_max_f32_e32 v236, v236, v237
	v_max_f32_e32 v236, 1.0, v236
	v_log_f32_e32 v236, v236
	s_nop 0
	v_add_f32_e32 v237, v195, v236
	v_cvt_pk_bf16_f32 v237, v237, v237
	v_and_b32_e32 v237, 0xffff0000, v237
	v_sub_f32_e32 v229, v195, v237
	v_mov_b32_e32 v195, v237
	v_exp_f32_e32 v232, v229
	v_xor_b32_e32 v237, 0x80000000, v237
	v_lshrrev_b32_e32 v237, 16, v237
	v_and_b32_e32 v248, v228, v237
	v_mul_f32_e32 v80, v80, v232
	v_mul_f32_e32 v81, v81, v232
	v_mul_f32_e32 v82, v82, v232
	v_mul_f32_e32 v83, v83, v232
	v_mul_f32_e32 v84, v84, v232
	v_mul_f32_e32 v85, v85, v232
	v_mul_f32_e32 v86, v86, v232
	v_mul_f32_e32 v87, v87, v232
	v_mul_f32_e32 v88, v88, v232
	v_mul_f32_e32 v89, v89, v232
	v_mul_f32_e32 v90, v90, v232
	v_mul_f32_e32 v91, v91, v232
	v_mul_f32_e32 v92, v92, v232
	v_mul_f32_e32 v93, v93, v232
	v_mul_f32_e32 v94, v94, v232
	v_mul_f32_e32 v95, v95, v232
	v_mul_f32_e32 v230, v230, v232
	v_pk_mul_f32 v[32:33], v[32:33], v[232:233] op_sel_hi:[1,0]
	v_pk_mul_f32 v[34:35], v[34:35], v[232:233] op_sel_hi:[1,0]
	v_pk_mul_f32 v[36:37], v[36:37], v[232:233] op_sel_hi:[1,0]
	v_pk_mul_f32 v[38:39], v[38:39], v[232:233] op_sel_hi:[1,0]
	v_pk_mul_f32 v[40:41], v[40:41], v[232:233] op_sel_hi:[1,0]
	v_pk_mul_f32 v[42:43], v[42:43], v[232:233] op_sel_hi:[1,0]
	v_pk_mul_f32 v[44:45], v[44:45], v[232:233] op_sel_hi:[1,0]
	v_pk_mul_f32 v[46:47], v[46:47], v[232:233] op_sel_hi:[1,0]
	v_pk_mul_f32 v[0:1], v[0:1], v[232:233] op_sel_hi:[1,0]
	v_pk_mul_f32 v[2:3], v[2:3], v[232:233] op_sel_hi:[1,0]
	v_pk_mul_f32 v[4:5], v[4:5], v[232:233] op_sel_hi:[1,0]
	v_pk_mul_f32 v[6:7], v[6:7], v[232:233] op_sel_hi:[1,0]
	v_pk_mul_f32 v[8:9], v[8:9], v[232:233] op_sel_hi:[1,0]
	v_pk_mul_f32 v[10:11], v[10:11], v[232:233] op_sel_hi:[1,0]
	v_pk_mul_f32 v[12:13], v[12:13], v[232:233] op_sel_hi:[1,0]
	v_pk_mul_f32 v[14:15], v[14:15], v[232:233] op_sel_hi:[1,0]
	v_mul_f32_e32 v193, v193, v232
	s_branch .Lat_back_bE
.Lat_resc_aO:
	s_nop 15
	v_max3_f32 v226, v96, v97, v98
	v_max3_f32 v227, v99, v100, v101
	v_max3_f32 v226, v226, v102, v103
	v_max3_f32 v227, v227, v104, v105
	v_max3_f32 v226, v226, v106, v107
	v_max3_f32 v227, v227, v108, v109
	v_max3_f32 v226, v226, v110, v111
	v_max_f32_e32 v226, v226, v227
	v_mov_b32_e32 v227, v226
	s_nop 1
	v_permlane32_swap_b32_e32 v226, v227
	v_max_f32_e32 v226, v226, v227
	v_max_f32_e32 v226, 1.0, v226
	v_log_f32_e32 v226, v226
	s_nop 0
	v_add_f32_e32 v227, v194, v226
	v_cvt_pk_bf16_f32 v227, v227, v227
	v_and_b32_e32 v227, 0xffff0000, v227
	v_sub_f32_e32 v229, v194, v227
	v_mov_b32_e32 v194, v227
	v_exp_f32_e32 v232, v229
	v_xor_b32_e32 v227, 0x80000000, v227
	v_lshrrev_b32_e32 v227, 16, v227
	v_and_b32_e32 v244, v228, v227
	v_mul_f32_e32 v96, v96, v232
	v_mul_f32_e32 v97, v97, v232
	v_mul_f32_e32 v98, v98, v232
	v_mul_f32_e32 v99, v99, v232
	v_mul_f32_e32 v100, v100, v232
	v_mul_f32_e32 v101, v101, v232
	v_mul_f32_e32 v102, v102, v232
	v_mul_f32_e32 v103, v103, v232
	v_mul_f32_e32 v104, v104, v232
	v_mul_f32_e32 v105, v105, v232
	v_mul_f32_e32 v106, v106, v232
	v_mul_f32_e32 v107, v107, v232
	v_mul_f32_e32 v108, v108, v232
	v_mul_f32_e32 v109, v109, v232
	v_mul_f32_e32 v110, v110, v232
	v_mul_f32_e32 v111, v111, v232
	v_mul_f32_e32 v230, v230, v232
	v_pk_mul_f32 v[16:17], v[16:17], v[232:233] op_sel_hi:[1,0]
	v_pk_mul_f32 v[18:19], v[18:19], v[232:233] op_sel_hi:[1,0]
	v_pk_mul_f32 v[20:21], v[20:21], v[232:233] op_sel_hi:[1,0]
	v_pk_mul_f32 v[22:23], v[22:23], v[232:233] op_sel_hi:[1,0]
	v_pk_mul_f32 v[24:25], v[24:25], v[232:233] op_sel_hi:[1,0]
	v_pk_mul_f32 v[26:27], v[26:27], v[232:233] op_sel_hi:[1,0]
	v_pk_mul_f32 v[28:29], v[28:29], v[232:233] op_sel_hi:[1,0]
	v_pk_mul_f32 v[30:31], v[30:31], v[232:233] op_sel_hi:[1,0]
	v_pk_mul_f32 v[48:49], v[48:49], v[232:233] op_sel_hi:[1,0]
	v_pk_mul_f32 v[50:51], v[50:51], v[232:233] op_sel_hi:[1,0]
	v_pk_mul_f32 v[52:53], v[52:53], v[232:233] op_sel_hi:[1,0]
	v_pk_mul_f32 v[54:55], v[54:55], v[232:233] op_sel_hi:[1,0]
	v_pk_mul_f32 v[56:57], v[56:57], v[232:233] op_sel_hi:[1,0]
	v_pk_mul_f32 v[58:59], v[58:59], v[232:233] op_sel_hi:[1,0]
	v_pk_mul_f32 v[60:61], v[60:61], v[232:233] op_sel_hi:[1,0]
	v_pk_mul_f32 v[62:63], v[62:63], v[232:233] op_sel_hi:[1,0]
	v_mul_f32_e32 v191, v191, v232
	s_branch .Lat_back_aO
.Lat_resc_bO:
	s_nop 15
	v_max3_f32 v236, v112, v113, v114
	v_max3_f32 v237, v115, v116, v117
	v_max3_f32 v236, v236, v118, v119
	v_max3_f32 v237, v237, v120, v121
	v_max3_f32 v236, v236, v122, v123
	v_max3_f32 v237, v237, v124, v125
	v_max3_f32 v236, v236, v126, v127
	v_max_f32_e32 v236, v236, v237
	v_mov_b32_e32 v237, v236
	s_nop 1
	v_permlane32_swap_b32_e32 v236, v237
	v_max_f32_e32 v236, v236, v237
	v_max_f32_e32 v236, 1.0, v236
	v_log_f32_e32 v236, v236
	s_nop 0
	v_add_f32_e32 v237, v195, v236
	v_cvt_pk_bf16_f32 v237, v237, v237
	v_and_b32_e32 v237, 0xffff0000, v237
	v_sub_f32_e32 v229, v195, v237
	v_mov_b32_e32 v195, v237
	v_exp_f32_e32 v232, v229
	v_xor_b32_e32 v237, 0x80000000, v237
	v_lshrrev_b32_e32 v237, 16, v237
	v_and_b32_e32 v248, v228, v237
	v_mul_f32_e32 v112, v112, v232
	v_mul_f32_e32 v113, v113, v232
	v_mul_f32_e32 v114, v114, v232
	v_mul_f32_e32 v115, v115, v232
	v_mul_f32_e32 v116, v116, v232
	v_mul_f32_e32 v117, v117, v232
	v_mul_f32_e32 v118, v118, v232
	v_mul_f32_e32 v119, v119, v232
	v_mul_f32_e32 v120, v120, v232
	v_mul_f32_e32 v121, v121, v232
	v_mul_f32_e32 v122, v122, v232
	v_mul_f32_e32 v123, v123, v232
	v_mul_f32_e32 v124, v124, v232
	v_mul_f32_e32 v125, v125, v232
	v_mul_f32_e32 v126, v126, v232
	v_mul_f32_e32 v127, v127, v232
	v_mul_f32_e32 v230, v230, v232
	v_pk_mul_f32 v[32:33], v[32:33], v[232:233] op_sel_hi:[1,0]
	v_pk_mul_f32 v[34:35], v[34:35], v[232:233] op_sel_hi:[1,0]
	v_pk_mul_f32 v[36:37], v[36:37], v[232:233] op_sel_hi:[1,0]
	v_pk_mul_f32 v[38:39], v[38:39], v[232:233] op_sel_hi:[1,0]
	v_pk_mul_f32 v[40:41], v[40:41], v[232:233] op_sel_hi:[1,0]
	v_pk_mul_f32 v[42:43], v[42:43], v[232:233] op_sel_hi:[1,0]
	v_pk_mul_f32 v[44:45], v[44:45], v[232:233] op_sel_hi:[1,0]
	v_pk_mul_f32 v[46:47], v[46:47], v[232:233] op_sel_hi:[1,0]
	v_pk_mul_f32 v[0:1], v[0:1], v[232:233] op_sel_hi:[1,0]
	v_pk_mul_f32 v[2:3], v[2:3], v[232:233] op_sel_hi:[1,0]
	v_pk_mul_f32 v[4:5], v[4:5], v[232:233] op_sel_hi:[1,0]
	v_pk_mul_f32 v[6:7], v[6:7], v[232:233] op_sel_hi:[1,0]
	v_pk_mul_f32 v[8:9], v[8:9], v[232:233] op_sel_hi:[1,0]
	v_pk_mul_f32 v[10:11], v[10:11], v[232:233] op_sel_hi:[1,0]
	v_pk_mul_f32 v[12:13], v[12:13], v[232:233] op_sel_hi:[1,0]
	v_pk_mul_f32 v[14:15], v[14:15], v[232:233] op_sel_hi:[1,0]
	v_mul_f32_e32 v193, v193, v232
	s_branch .Lat_back_bO
